# speedup vs baseline: 1.0045x; 1.0045x over previous
; #define QK_FENCE() __builtin_amdgcn_sched_barrier(0x406)
; DI void partialSM(f32x16& p0, f32x16& p1, float& m_reg, float& mn, float& alpha) {
;     ...
;   const float mnC = -mn * C;
; #pragma unroll
;   for (int r = 0; r < 16; ++r) p0[r] = fmaf(p0[r], C, mnC);
; #pragma unroll
;   for (int r = 0; r < 16; ++r) p1[r] = fmaf(p1[r], C, mnC);
; #pragma unroll
;   for (int r = 0; r < 16; ++r) p0[r] = __builtin_amdgcn_exp2f(p0[r]);
; }
; DI void finishSM(f32x16& p0, f32x16& p1, float alpha, float& l_reg, bf16x8& pa0, bf16x8& pa1, bf16x8& pa2, bf16x8& pa3) {
; #pragma unroll
;   for (int r = 0; r < 16; ++r) p1[r] = __builtin_amdgcn_exp2f(p1[r]);
;   float ps = 0;
; #pragma unroll
;   for (int r = 0; r < 16; ++r) ps += p0[r];
; #pragma unroll
;   for (int r = 0; r < 16; ++r) ps += p1[r];
;   { auto rr = __builtin_amdgcn_permlane32_swap(__float_as_uint(ps), __float_as_uint(ps), false, false);
;     ps = __uint_as_float(rr[0]) + __uint_as_float(rr[1]); }
;   l_reg = l_reg * alpha + ps;
; DI void qkt12(f32x16& p0, f32x16& p1, const char* Kt, const char* Rt, const int* ko, const int* ro, const bf16x8* qr) {
;   { const f32x16 z = {0.f, 0.f, 0.f, 0.f, 0.f, 0.f, 0.f, 0.f, 0.f, 0.f, 0.f, 0.f, 0.f, 0.f, 0.f, 0.f}; p0 = z; p1 = z; }
;   const char* kp[4] = {Kt + ko[0], Kt + ko[1], Kt + ko[2], Kt + ko[3]};
;   const char* rp[4] = {Rt + ro[0], Rt + ro[1], Rt + ro[2], Rt + ro[3]};
;   bf16x8 ka[2], kb[2];
;   ka[0] = *reinterpret_cast<const bf16x8*>(kp[0]); kb[0] = *reinterpret_cast<const bf16x8*>(kp[0] + 8192);
; #pragma unroll
;   for (int d0 = 0; d0 < 12; ++d0) {
;     if (d0 + 1 < 12) { const int d1 = d0 + 1;
;       if (d1 < 8) { ka[d1 & 1] = *reinterpret_cast<const bf16x8*>(kp[d1 & 3] + (d1 >> 2) * 128); kb[d1 & 1] = *reinterpret_cast<const bf16x8*>(kp[d1 & 3] + (d1 >> 2) * 128 + 8192); }
;       else { ka[d1 & 1] = *reinterpret_cast<const bf16x8*>(rp[d1 - 8]); kb[d1 & 1] = *reinterpret_cast<const bf16x8*>(rp[d1 - 8] + 4096); } }
;     QK_FENCE();
;     p0 = __builtin_amdgcn_mfma_f32_32x32x16_bf16(ka[d0 & 1], qr[d0], p0, 0, 0, 0);
;     p1 = __builtin_amdgcn_mfma_f32_32x32x16_bf16(kb[d0 & 1], qr[d0], p1, 0, 0, 0);
;     QK_FENCE();
;   }
.LBB0_128:
	s_add_i32 s2, s12, -1
	s_cmp_ge_u32 s2, s52
	s_cbranch_scc1 .Lattn_bb2_nodma
	v_cndmask_b32_e64 v160, v160, v187, s[38:39]
	s_add_i32 s2, s42, 0xa000
	s_cmp_lg_u32 s61, 2
	s_cselect_b32 s2, s2, 0
	s_add_i32 s6, s2, 16
	v_add_u32_e32 v213, s6, v176
	ds_read_b128 v[222:225], v213 offset:16384
	v_add_u32_e32 v230, s6, v179
	ds_read_b128 v[226:229], v213 offset:24576
	ds_read_b128 v[214:217], v230 offset:16384
	ds_read_b128 v[218:221], v230 offset:24576
	v_add_u32_e32 v231, s6, v180
	v_add_u32_e32 v234, s6, v181
	v_mul_f32_e32 v197, 0xbdd53b94, v160
	v_fmamk_f32 v161, v94, 0x3dd53b94, v197
	v_fmamk_f32 v194, v80, 0x3dd53b94, v197
	v_fmamk_f32 v196, v81, 0x3dd53b94, v197
	v_fmamk_f32 v192, v82, 0x3dd53b94, v197
	v_fmamk_f32 v195, v83, 0x3dd53b94, v197
	v_fmamk_f32 v187, v84, 0x3dd53b94, v197
	v_fmamk_f32 v193, v85, 0x3dd53b94, v197
	v_fmamk_f32 v169, v86, 0x3dd53b94, v197
	v_fmamk_f32 v190, v87, 0x3dd53b94, v197
	v_fmamk_f32 v166, v88, 0x3dd53b94, v197
	v_fmamk_f32 v168, v89, 0x3dd53b94, v197
	v_fmamk_f32 v164, v90, 0x3dd53b94, v197
	s_waitcnt lgkmcnt(3)
	v_fmamk_f32 v167, v91, 0x3dd53b94, v197
	v_fmamk_f32 v162, v92, 0x3dd53b94, v197
	v_fmamk_f32 v165, v93, 0x3dd53b94, v197
	v_fmamk_f32 v163, v95, 0x3dd53b94, v197
	v_mfma_f32_32x32x16_bf16 v[80:95], v[222:225], v[134:137], 0
	v_fmamk_f32 v208, v74, 0x3dd53b94, v197
	v_fmamk_f32 v209, v75, 0x3dd53b94, v197
	v_fmamk_f32 v198, v64, 0x3dd53b94, v197
	v_fmamk_f32 v199, v65, 0x3dd53b94, v197
	v_fmamk_f32 v200, v66, 0x3dd53b94, v197
	v_fmamk_f32 v201, v67, 0x3dd53b94, v197
	s_waitcnt lgkmcnt(1)
	v_mfma_f32_32x32x16_bf16 v[80:95], v[214:217], v[130:133], v[80:95]
	v_fmamk_f32 v202, v68, 0x3dd53b94, v197
	v_fmamk_f32 v203, v69, 0x3dd53b94, v197
	v_fmamk_f32 v204, v70, 0x3dd53b94, v197
	v_fmamk_f32 v205, v71, 0x3dd53b94, v197
	v_fmamk_f32 v206, v72, 0x3dd53b94, v197
	v_fmamk_f32 v207, v73, 0x3dd53b94, v197
	v_fmamk_f32 v210, v76, 0x3dd53b94, v197
	v_fmamk_f32 v211, v77, 0x3dd53b94, v197
	v_fmamk_f32 v212, v78, 0x3dd53b94, v197
	v_fmac_f32_e32 v197, 0x3dd53b94, v79
	v_mfma_f32_32x32x16_bf16 v[64:79], v[226:229], v[134:137], 0
	v_add_u32_e32 v240, s44, v178
	v_exp_f32_e32 v161, v161
	v_readfirstlane_b32 s2, v240
	s_mov_b64 s[0:1], 0x1bc00100
	v_lshl_add_u64 v[238:239], v[158:159], 0, s[0:1]
	s_mov_b32 m0, s2
	v_exp_f32_e32 v194, v194
	global_load_lds_dwordx4 v[238:239], off
	ds_read_b128 v[222:225], v231 offset:16384
	ds_read_b128 v[226:229], v231 offset:24576
	s_waitcnt lgkmcnt(2)
	v_mfma_f32_32x32x16_bf16 v[64:79], v[218:221], v[130:133], v[64:79]
	ds_read_b128 v[214:217], v234 offset:16384
	ds_read_b128 v[218:221], v234 offset:24576
	v_exp_f32_e32 v196, v196
	v_exp_f32_e32 v192, v192
	v_exp_f32_e32 v195, v195
	s_waitcnt lgkmcnt(3)
	v_mfma_f32_32x32x16_bf16 v[80:95], v[222:225], v[126:129], v[80:95]
	v_exp_f32_e32 v187, v187
	v_exp_f32_e32 v193, v193
	v_exp_f32_e32 v169, v169
	s_waitcnt lgkmcnt(2)
	v_mfma_f32_32x32x16_bf16 v[64:79], v[226:229], v[126:129], v[64:79]
	ds_read_b128 v[222:225], v213 offset:16512
	ds_read_b128 v[226:229], v213 offset:24704
	v_add_u32_e32 v213, s6, v182
	v_exp_f32_e32 v190, v190
	v_exp_f32_e32 v166, v166
	s_waitcnt lgkmcnt(3)
	v_mfma_f32_32x32x16_bf16 v[80:95], v[214:217], v[114:117], v[80:95]
	v_add_u32_e32 v242, 0x2000, v240
	s_mov_b64 s[0:1], 0x1bc20100
	v_lshl_add_u64 v[238:239], v[158:159], 0, s[0:1]
	v_readfirstlane_b32 s2, v242
	s_mov_b32 m0, s2
	v_exp_f32_e32 v168, v168
	global_load_lds_dwordx4 v[238:239], off
	s_waitcnt lgkmcnt(2)
	v_mfma_f32_32x32x16_bf16 v[64:79], v[218:221], v[114:117], v[64:79]
	ds_read_b128 v[214:217], v230 offset:16512
	ds_read_b128 v[218:221], v230 offset:24704
	v_exp_f32_e32 v164, v164
	v_exp_f32_e32 v167, v167
	v_exp_f32_e32 v162, v162
	s_waitcnt lgkmcnt(3)
	v_mfma_f32_32x32x16_bf16 v[80:95], v[222:225], v[110:113], v[80:95]
	v_exp_f32_e32 v165, v165
	v_exp_f32_e32 v163, v163
	v_exp_f32_e32 v198, v198
	s_waitcnt lgkmcnt(2)
	v_mfma_f32_32x32x16_bf16 v[64:79], v[226:229], v[110:113], v[64:79]
	ds_read_b128 v[222:225], v231 offset:16512
	ds_read_b128 v[226:229], v231 offset:24704
	v_exp_f32_e32 v199, v199
	v_exp_f32_e32 v200, v200
	v_exp_f32_e32 v201, v201
	s_waitcnt lgkmcnt(3)
	v_mfma_f32_32x32x16_bf16 v[80:95], v[214:217], v[106:109], v[80:95]
	v_add_u32_e32 v242, 0x4000, v240
	s_mov_b64 s[0:1], 0x1bc00000
	v_lshl_add_u64 v[238:239], v[156:157], 0, s[0:1]
	v_readfirstlane_b32 s2, v242
	s_mov_b32 m0, s2
	v_exp_f32_e32 v202, v202
	global_load_lds_dwordx4 v[238:239], off
	s_waitcnt lgkmcnt(2)
	v_mfma_f32_32x32x16_bf16 v[64:79], v[218:221], v[106:109], v[64:79]
	ds_read_b128 v[214:217], v234 offset:16512
	ds_read_b128 v[218:221], v234 offset:24704
	v_exp_f32_e32 v203, v203
	v_exp_f32_e32 v204, v204
	v_exp_f32_e32 v205, v205
	s_waitcnt lgkmcnt(3)
	v_mfma_f32_32x32x16_bf16 v[80:95], v[222:225], v[102:105], v[80:95]
	v_exp_f32_e32 v206, v206
	v_exp_f32_e32 v207, v207
	v_exp_f32_e32 v210, v210
	s_waitcnt lgkmcnt(2)
	v_mfma_f32_32x32x16_bf16 v[64:79], v[226:229], v[102:105], v[64:79]
	ds_read_b128 v[222:225], v213 offset:32768
	ds_read_b128 v[226:229], v213 offset:36864
	v_add_u32_e32 v213, s6, v183
	v_exp_f32_e32 v211, v211
	v_exp_f32_e32 v212, v212
	s_waitcnt lgkmcnt(3)
	v_mfma_f32_32x32x16_bf16 v[80:95], v[214:217], v[98:101], v[80:95]
	v_add_u32_e32 v242, 0x6000, v240
	s_mov_b64 s[0:1], 0x1bc20000
	v_lshl_add_u64 v[238:239], v[156:157], 0, s[0:1]
	v_readfirstlane_b32 s2, v242
	s_mov_b32 m0, s2
	v_exp_f32_e32 v235, v208
	global_load_lds_dwordx4 v[238:239], off
	s_waitcnt lgkmcnt(2)
; #define SBAR() __builtin_amdgcn_sched_barrier(0)
; template <int OFF> DI s16x4 tr_read(int vb) { s16x4 r; asm volatile("ds_read_b64_tr_b16 %0, %1 offset:%2" : "=&v"(r) : "v"(vb), "i"(OFF) : "memory"); return r; }
; DI void finishSM(f32x16& p0, f32x16& p1, float alpha, float& l_reg, bf16x8& pa0, bf16x8& pa1, bf16x8& pa2, bf16x8& pa3) {
;     ...
;   float ps = 0;
; #pragma unroll
;   for (int r = 0; r < 16; ++r) ps += p0[r];
; #pragma unroll
;   for (int r = 0; r < 16; ++r) ps += p1[r];
;   { auto rr = __builtin_amdgcn_permlane32_swap(__float_as_uint(ps), __float_as_uint(ps), false, false);
;     ps = __uint_as_float(rr[0]) + __uint_as_float(rr[1]); }
;   l_reg = l_reg * alpha + ps;
;     ...
;   PK4(p0, 0, pa0); PK4(p0, 8, pa1); PK4(p1, 0, pa2); PK4(p1, 8, pa3);
;     ...
; }
; template <int D0> DI void pv_one(f32x16& od, int vb, bf16x8 pa0, bf16x8 pa1, bf16x8 pa2, bf16x8 pa3) {
;   const s16x4 l0 = tr_read<v_rd_off(D0, 0, 0)>(vb), h0 = tr_read<v_rd_off(D0, 0, 1)>(vb), l1 = tr_read<v_rd_off(D0, 1, 0)>(vb), h1 = tr_read<v_rd_off(D0, 1, 1)>(vb);
;   const s16x4 l2 = tr_read<v_rd_off(D0, 2, 0)>(vb), h2 = tr_read<v_rd_off(D0, 2, 1)>(vb), l3 = tr_read<v_rd_off(D0, 3, 0)>(vb), h3 = tr_read<v_rd_off(D0, 3, 1)>(vb);
;   asm volatile("s_waitcnt lgkmcnt(0)" ::: "memory"); SBAR();
;     ...
;   od = __builtin_amdgcn_mfma_f32_32x32x16_bf16(pa0, PK(l0, h0), od, 0, 0, 0);
;   od = __builtin_amdgcn_mfma_f32_32x32x16_bf16(pa1, PK(l1, h1), od, 0, 0, 0);
;   od = __builtin_amdgcn_mfma_f32_32x32x16_bf16(pa2, PK(l2, h2), od, 0, 0, 0);
;   od = __builtin_amdgcn_mfma_f32_32x32x16_bf16(pa3, PK(l3, h3), od, 0, 0, 0);
;     ...
; }
; DI void pv_d0(f32x16* o, int vb, bf16x8 pa0, bf16x8 pa1, bf16x8 pa2, bf16x8 pa3) {
;   pv_one<0>(o[0], vb, pa0, pa1, pa2, pa3); pv_one<1>(o[1], vb, pa0, pa1, pa2, pa3); pv_one<2>(o[2], vb, pa0, pa1, pa2, pa3); pv_one<3>(o[3], vb, pa0, pa1, pa2, pa3);
	v_mfma_f32_32x32x16_bf16 v[64:79], v[218:221], v[98:101], v[64:79]
	ds_read_b128 v[214:217], v213 offset:32768
	ds_read_b128 v[218:221], v213 offset:36864
	v_add_u32_e32 v213, s6, v184
	v_exp_f32_e32 v237, v197
	v_add_f32_e32 v197, 0, v194
	v_add_f32_e32 v197, v196, v197
	v_add_f32_e32 v197, v192, v197
	s_waitcnt lgkmcnt(3)
	v_mfma_f32_32x32x16_bf16 v[80:95], v[222:225], v[122:125], v[80:95]
	v_add_f32_e32 v197, v195, v197
	v_add_f32_e32 v197, v187, v197
	v_add_f32_e32 v197, v193, v197
	v_add_f32_e32 v197, v169, v197
	v_add_f32_e32 v197, v190, v197
	v_add_f32_e32 v197, v166, v197
	s_waitcnt lgkmcnt(2)
	v_mfma_f32_32x32x16_bf16 v[64:79], v[226:229], v[122:125], v[64:79]
	ds_read_b128 v[222:225], v213 offset:32768
	ds_read_b128 v[226:229], v213 offset:36864
	v_add_u32_e32 v213, s6, v185
	v_add_f32_e32 v197, v168, v197
	v_add_f32_e32 v197, v164, v197
	v_add_f32_e32 v197, v167, v197
	v_add_f32_e32 v197, v162, v197
	v_add_f32_e32 v197, v165, v197
	s_waitcnt lgkmcnt(3)
	v_mfma_f32_32x32x16_bf16 v[80:95], v[214:217], v[142:145], v[80:95]
	v_add_u32_e32 v242, 0x8000, v240
	s_mov_b64 s[0:1], 0x1fb46000
	v_lshl_add_u64 v[238:239], v[154:155], 0, s[0:1]
	v_readfirstlane_b32 s2, v242
	s_mov_b32 m0, s2
	v_add_f32_e32 v197, v161, v197
	global_load_lds_dwordx4 v[238:239], off
	s_movk_i32 s0, 0x410
	s_movk_i32 s1, 0x1800
	v_add_f32_e32 v197, v163, v197
	v_add_f32_e32 v197, v198, v197
	s_waitcnt lgkmcnt(2)
	v_mfma_f32_32x32x16_bf16 v[64:79], v[218:221], v[142:145], v[64:79]
	ds_read_b128 v[214:217], v213 offset:32768
	ds_read_b128 v[218:221], v213 offset:36864
	v_add_f32_e32 v197, v199, v197
	v_add_f32_e32 v197, v200, v197
	v_add_f32_e32 v197, v201, v197
	v_add_f32_e32 v197, v202, v197
	v_add_f32_e32 v197, v203, v197
	v_add_f32_e32 v197, v204, v197
	s_waitcnt lgkmcnt(3)
	v_mfma_f32_32x32x16_bf16 v[80:95], v[222:225], v[118:121], v[80:95]
	v_exp_f32_e32 v241, v209
	v_add_f32_e32 v197, v205, v197
	v_add_f32_e32 v197, v206, v197
	v_add_f32_e32 v197, v207, v197
	v_add_f32_e32 v197, v235, v197
	s_waitcnt lgkmcnt(2)
	v_mfma_f32_32x32x16_bf16 v[64:79], v[226:229], v[118:121], v[64:79]
	v_add_f32_e32 v197, v241, v197
	v_add_f32_e32 v197, v210, v197
	v_add_f32_e32 v197, v211, v197
	v_add_f32_e32 v197, v212, v197
	v_add_f32_e32 v208, v237, v197
	v_mov_b32_e32 v209, v208
	s_waitcnt lgkmcnt(1)
	v_mfma_f32_32x32x16_bf16 v[80:95], v[214:217], v[138:141], v[80:95]
	v_permlane32_swap_b32_e32 v208, v209
	v_cvt_pk_bf16_f32 v194, v194, v196
	v_cvt_pk_bf16_f32 v195, v192, v195
	v_cvt_pk_bf16_f32 v196, v187, v193
	v_cvt_pk_bf16_f32 v197, v169, v190
	v_cvt_pk_bf16_f32 v166, v166, v168
	s_waitcnt lgkmcnt(0)
	v_mfma_f32_32x32x16_bf16 v[64:79], v[218:221], v[138:141], v[64:79]
	v_cvt_pk_bf16_f32 v167, v164, v167
	v_cvt_pk_bf16_f32 v168, v162, v165
	v_cvt_pk_bf16_f32 v169, v161, v163
	v_add_u32_e32 v161, s42, v174
	v_cvt_pk_bf16_f32 v162, v198, v199
	v_cvt_pk_bf16_f32 v163, v200, v201
	v_cvt_pk_bf16_f32 v164, v202, v203
	ds_read_b64_tr_b16 v[202:203], v161 offset:0
	v_cvt_pk_bf16_f32 v165, v204, v205
	ds_read_b64_tr_b16 v[204:205], v161 offset:0x800
	v_cvt_pk_bf16_f32 v198, v206, v207
	v_cvt_pk_bf16_f32 v199, v235, v241
	v_cvt_pk_bf16_f32 v200, v210, v211
	ds_read_b64_tr_b16 v[210:211], v161 offset:0x1000
	v_cvt_pk_bf16_f32 v201, v212, v237
	ds_read_b64_tr_b16 v[212:213], v161 offset:0x1800
	ds_read_b64_tr_b16 v[214:215], v161 offset:0x2000
	ds_read_b64_tr_b16 v[216:217], v161 offset:0x2800
	ds_read_b64_tr_b16 v[218:219], v161 offset:0x3000
	ds_read_b64_tr_b16 v[220:221], v161 offset:0x3800
	s_waitcnt lgkmcnt(6)
	v_permlane32_swap_b32_e32 v194, v196
	v_permlane32_swap_b32_e32 v195, v197
	v_permlane32_swap_b32_e32 v166, v168
	v_permlane32_swap_b32_e32 v167, v169
	v_mfma_f32_32x32x16_bf16 v[0:15], v[194:197], v[202:205], v[0:15]
	ds_read_b64_tr_b16 v[202:203], v161 offset:0x200
	ds_read_b64_tr_b16 v[204:205], v161 offset:0xa00
	v_permlane32_swap_b32_e32 v162, v164
	v_permlane32_swap_b32_e32 v163, v165
	v_permlane32_swap_b32_e32 v198, v200
	v_permlane32_swap_b32_e32 v199, v201
	v_max_f32_e32 v235, v81, v81
	v_max_f32_e32 v237, v80, v80
	s_waitcnt lgkmcnt(6)
	v_mfma_f32_32x32x16_bf16 v[0:15], v[166:169], v[210:213], v[0:15]
	ds_read_b64_tr_b16 v[210:211], v161 offset:0x1200
	ds_read_b64_tr_b16 v[212:213], v161 offset:0x1a00
	v_max_f32_e32 v235, v237, v235
	v_max3_f32 v235, v235, v82, v83
	v_max3_f32 v235, v235, v84, v85
	v_max3_f32 v235, v235, v86, v87
	v_max3_f32 v235, v235, v88, v89
	v_max3_f32 v235, v235, v90, v91
	s_waitcnt lgkmcnt(6)
	v_mfma_f32_32x32x16_bf16 v[0:15], v[162:165], v[214:217], v[0:15]
	ds_read_b64_tr_b16 v[214:215], v161 offset:0x2200
	ds_read_b64_tr_b16 v[216:217], v161 offset:0x2a00
	v_max3_f32 v235, v235, v92, v93
	v_max3_f32 v235, v235, v94, v95
	v_max3_f32 v235, v235, v64, v65
	v_max3_f32 v235, v235, v66, v67
	v_max3_f32 v235, v235, v68, v69
	v_max3_f32 v235, v235, v70, v71
	s_waitcnt lgkmcnt(6)
	v_mfma_f32_32x32x16_bf16 v[0:15], v[198:201], v[218:221], v[0:15]
	ds_read_b64_tr_b16 v[218:219], v161 offset:0x3200
	ds_read_b64_tr_b16 v[220:221], v161 offset:0x3a00
	v_max3_f32 v235, v235, v72, v73
	v_max3_f32 v235, v235, v74, v75
	v_max3_f32 v235, v235, v76, v77
	v_max3_f32 v235, v235, v78, v79
	v_mov_b32_e32 v237, v235
	s_waitcnt lgkmcnt(6)
	v_mfma_f32_32x32x16_bf16 v[48:63], v[194:197], v[202:205], v[48:63]
	ds_read_b64_tr_b16 v[202:203], v161 offset:0x400
	ds_read_b64_tr_b16 v[204:205], v161 offset:0xc00
	v_permlane32_swap_b32_e32 v235, v237
	v_max_f32_e32 v237, v237, v237
	v_max_f32_e32 v235, v235, v235
	s_waitcnt lgkmcnt(6)
	v_mfma_f32_32x32x16_bf16 v[48:63], v[166:169], v[210:213], v[48:63]
	ds_read_b64_tr_b16 v[210:211], v161 offset:0x1400
	ds_read_b64_tr_b16 v[212:213], v161 offset:0x1c00
	s_waitcnt lgkmcnt(6)
	v_mfma_f32_32x32x16_bf16 v[48:63], v[162:165], v[214:217], v[48:63]
	ds_read_b64_tr_b16 v[214:215], v161 offset:0x2400
	ds_read_b64_tr_b16 v[216:217], v161 offset:0x2c00
	s_waitcnt lgkmcnt(6)
	v_mfma_f32_32x32x16_bf16 v[48:63], v[198:201], v[218:221], v[48:63]
	ds_read_b64_tr_b16 v[218:219], v161 offset:0x3400
	ds_read_b64_tr_b16 v[220:221], v161 offset:0x3c00
	s_waitcnt lgkmcnt(6)
	v_mfma_f32_32x32x16_bf16 v[32:47], v[194:197], v[202:205], v[32:47]
	ds_read_b64_tr_b16 v[202:203], v161 offset:0x600
	ds_read_b64_tr_b16 v[204:205], v161 offset:0xe00
	s_waitcnt lgkmcnt(6)
	v_mfma_f32_32x32x16_bf16 v[32:47], v[166:169], v[210:213], v[32:47]
	ds_read_b64_tr_b16 v[210:211], v161 offset:0x1600
	ds_read_b64_tr_b16 v[212:213], v161 offset:0x1e00
	s_waitcnt lgkmcnt(6)
	v_mfma_f32_32x32x16_bf16 v[32:47], v[162:165], v[214:217], v[32:47]
	ds_read_b64_tr_b16 v[214:215], v161 offset:0x2600
	ds_read_b64_tr_b16 v[216:217], v161 offset:0x2e00
	s_waitcnt lgkmcnt(6)
	v_mfma_f32_32x32x16_bf16 v[32:47], v[198:201], v[218:221], v[32:47]
	ds_read_b64_tr_b16 v[218:219], v161 offset:0x3600
	ds_read_b64_tr_b16 v[220:221], v161 offset:0x3e00
	v_max_f32_e32 v161, v235, v237
	v_sub_f32_e32 v237, v161, v160
	s_waitcnt vmcnt(0)
	s_waitcnt vmcnt(0)
	s_waitcnt lgkmcnt(0)
	s_barrier
; #define SBAR() __builtin_amdgcn_sched_barrier(0)
; template <int OFF> DI s16x4 tr_read(int vb) { s16x4 r; asm volatile("ds_read_b64_tr_b16 %0, %1 offset:%2" : "=&v"(r) : "v"(vb), "i"(OFF) : "memory"); return r; }
; DI void partialSM(f32x16& p0, f32x16& p1, float& m_reg, float& mn, float& alpha) {
;     ...
;   const float mnC = -mn * C;
; #pragma unroll
;   for (int r = 0; r < 16; ++r) p0[r] = fmaf(p0[r], C, mnC);
; #pragma unroll
;   for (int r = 0; r < 16; ++r) p1[r] = fmaf(p1[r], C, mnC);
; #pragma unroll
;   for (int r = 0; r < 16; ++r) p0[r] = __builtin_amdgcn_exp2f(p0[r]);
; }
; DI void finishSM(f32x16& p0, f32x16& p1, float alpha, float& l_reg, bf16x8& pa0, bf16x8& pa1, bf16x8& pa2, bf16x8& pa3) {
; #pragma unroll
;   for (int r = 0; r < 16; ++r) p1[r] = __builtin_amdgcn_exp2f(p1[r]);
;   float ps = 0;
; #pragma unroll
;   for (int r = 0; r < 16; ++r) ps += p0[r];
; #pragma unroll
;   for (int r = 0; r < 16; ++r) ps += p1[r];
;   { auto rr = __builtin_amdgcn_permlane32_swap(__float_as_uint(ps), __float_as_uint(ps), false, false);
;     ps = __uint_as_float(rr[0]) + __uint_as_float(rr[1]); }
;   l_reg = l_reg * alpha + ps;
; template <int D0> DI void pv_one(f32x16& od, int vb, bf16x8 pa0, bf16x8 pa1, bf16x8 pa2, bf16x8 pa3) {
;   const s16x4 l0 = tr_read<v_rd_off(D0, 0, 0)>(vb), h0 = tr_read<v_rd_off(D0, 0, 1)>(vb), l1 = tr_read<v_rd_off(D0, 1, 0)>(vb), h1 = tr_read<v_rd_off(D0, 1, 1)>(vb);
;   const s16x4 l2 = tr_read<v_rd_off(D0, 2, 0)>(vb), h2 = tr_read<v_rd_off(D0, 2, 1)>(vb), l3 = tr_read<v_rd_off(D0, 3, 0)>(vb), h3 = tr_read<v_rd_off(D0, 3, 1)>(vb);
;   asm volatile("s_waitcnt lgkmcnt(0)" ::: "memory"); SBAR();
;     ...
;   od = __builtin_amdgcn_mfma_f32_32x32x16_bf16(pa0, PK(l0, h0), od, 0, 0, 0);
;   od = __builtin_amdgcn_mfma_f32_32x32x16_bf16(pa1, PK(l1, h1), od, 0, 0, 0);
;   od = __builtin_amdgcn_mfma_f32_32x32x16_bf16(pa2, PK(l2, h2), od, 0, 0, 0);
;   od = __builtin_amdgcn_mfma_f32_32x32x16_bf16(pa3, PK(l3, h3), od, 0, 0, 0);
;     ...
; }
; DI void pv_d0(f32x16* o, int vb, bf16x8 pa0, bf16x8 pa1, bf16x8 pa2, bf16x8 pa3) {
;   pv_one<0>(o[0], vb, pa0, pa1, pa2, pa3); pv_one<1>(o[1], vb, pa0, pa1, pa2, pa3); pv_one<2>(o[2], vb, pa0, pa1, pa2, pa3); pv_one<3>(o[3], vb, pa0, pa1, pa2, pa3);
	v_mfma_f32_32x32x16_bf16 v[16:31], v[194:197], v[202:205], v[16:31]
	v_mfma_f32_32x32x16_bf16 v[16:31], v[166:169], v[210:213], v[16:31]
	v_mfma_f32_32x32x16_bf16 v[16:31], v[162:165], v[214:217], v[16:31]
	v_mfma_f32_32x32x16_bf16 v[16:31], v[198:201], v[218:221], v[16:31]
	v_cmp_ge_f32_e32 vcc, s65, v237
	s_cmp_eq_u64 vcc, exec
	s_cselect_b64 s[38:39], -1, 0
	s_cmp_ge_u32 s12, s52
	s_cselect_b64 s[42:43], -1, 0
	s_and_b64 vcc, exec, s[42:43]
	s_branch .Lattn_bb2_join
.Lattn_bb2_nodma:
	v_cndmask_b32_e64 v160, v160, v187, s[38:39]
	s_add_i32 s2, s42, 0xa000
	s_cmp_lg_u32 s61, 2
	s_cselect_b32 s2, s2, 0
	s_add_i32 s6, s2, 16
	v_add_u32_e32 v213, s6, v176
	ds_read_b128 v[222:225], v213 offset:16384
	v_add_u32_e32 v230, s6, v179
	ds_read_b128 v[226:229], v213 offset:24576
	ds_read_b128 v[214:217], v230 offset:16384
	ds_read_b128 v[218:221], v230 offset:24576
	v_add_u32_e32 v231, s6, v180
	v_add_u32_e32 v234, s6, v181
	v_mul_f32_e32 v197, 0xbdd53b94, v160
	v_fmamk_f32 v161, v94, 0x3dd53b94, v197
	v_fmamk_f32 v194, v80, 0x3dd53b94, v197
	v_fmamk_f32 v196, v81, 0x3dd53b94, v197
	v_fmamk_f32 v192, v82, 0x3dd53b94, v197
	v_fmamk_f32 v195, v83, 0x3dd53b94, v197
	v_fmamk_f32 v187, v84, 0x3dd53b94, v197
	v_fmamk_f32 v193, v85, 0x3dd53b94, v197
	v_fmamk_f32 v169, v86, 0x3dd53b94, v197
	v_fmamk_f32 v190, v87, 0x3dd53b94, v197
	v_fmamk_f32 v166, v88, 0x3dd53b94, v197
	v_fmamk_f32 v168, v89, 0x3dd53b94, v197
	v_fmamk_f32 v164, v90, 0x3dd53b94, v197
	s_waitcnt lgkmcnt(3)
	v_fmamk_f32 v167, v91, 0x3dd53b94, v197
	v_fmamk_f32 v162, v92, 0x3dd53b94, v197
	v_fmamk_f32 v165, v93, 0x3dd53b94, v197
	v_fmamk_f32 v163, v95, 0x3dd53b94, v197
	v_mfma_f32_32x32x16_bf16 v[80:95], v[222:225], v[134:137], 0
	v_fmamk_f32 v208, v74, 0x3dd53b94, v197
	v_fmamk_f32 v209, v75, 0x3dd53b94, v197
	v_fmamk_f32 v198, v64, 0x3dd53b94, v197
	v_fmamk_f32 v199, v65, 0x3dd53b94, v197
	v_fmamk_f32 v200, v66, 0x3dd53b94, v197
	v_fmamk_f32 v201, v67, 0x3dd53b94, v197
	s_waitcnt lgkmcnt(1)
	v_mfma_f32_32x32x16_bf16 v[80:95], v[214:217], v[130:133], v[80:95]
	v_fmamk_f32 v202, v68, 0x3dd53b94, v197
	v_fmamk_f32 v203, v69, 0x3dd53b94, v197
	v_fmamk_f32 v204, v70, 0x3dd53b94, v197
	v_fmamk_f32 v205, v71, 0x3dd53b94, v197
	v_fmamk_f32 v206, v72, 0x3dd53b94, v197
	v_fmamk_f32 v207, v73, 0x3dd53b94, v197
	v_fmamk_f32 v210, v76, 0x3dd53b94, v197
	v_fmamk_f32 v211, v77, 0x3dd53b94, v197
	v_fmamk_f32 v212, v78, 0x3dd53b94, v197
	v_fmac_f32_e32 v197, 0x3dd53b94, v79
	v_mfma_f32_32x32x16_bf16 v[64:79], v[226:229], v[134:137], 0
	ds_read_b128 v[222:225], v231 offset:16384
	ds_read_b128 v[226:229], v231 offset:24576
	v_exp_f32_e32 v161, v161
	v_exp_f32_e32 v194, v194
	v_exp_f32_e32 v196, v196
	s_waitcnt lgkmcnt(2)
	v_mfma_f32_32x32x16_bf16 v[64:79], v[218:221], v[130:133], v[64:79]
	ds_read_b128 v[214:217], v234 offset:16384
	ds_read_b128 v[218:221], v234 offset:24576
	v_exp_f32_e32 v192, v192
	v_exp_f32_e32 v195, v195
	v_exp_f32_e32 v187, v187
	s_waitcnt lgkmcnt(3)
	v_mfma_f32_32x32x16_bf16 v[80:95], v[222:225], v[126:129], v[80:95]
	v_exp_f32_e32 v193, v193
	v_exp_f32_e32 v169, v169
	v_exp_f32_e32 v190, v190
	s_waitcnt lgkmcnt(2)
	v_mfma_f32_32x32x16_bf16 v[64:79], v[226:229], v[126:129], v[64:79]
	ds_read_b128 v[222:225], v213 offset:16512
	ds_read_b128 v[226:229], v213 offset:24704
	v_add_u32_e32 v213, s6, v182
	v_exp_f32_e32 v166, v166
	v_exp_f32_e32 v168, v168
	s_waitcnt lgkmcnt(3)
	v_mfma_f32_32x32x16_bf16 v[80:95], v[214:217], v[114:117], v[80:95]
	v_exp_f32_e32 v164, v164
	v_exp_f32_e32 v167, v167
	v_exp_f32_e32 v162, v162
	s_waitcnt lgkmcnt(2)
	v_mfma_f32_32x32x16_bf16 v[64:79], v[218:221], v[114:117], v[64:79]
	ds_read_b128 v[214:217], v230 offset:16512
	ds_read_b128 v[218:221], v230 offset:24704
	v_exp_f32_e32 v165, v165
	v_exp_f32_e32 v163, v163
	v_exp_f32_e32 v198, v198
	s_waitcnt lgkmcnt(3)
	v_mfma_f32_32x32x16_bf16 v[80:95], v[222:225], v[110:113], v[80:95]
	v_exp_f32_e32 v199, v199
	v_exp_f32_e32 v200, v200
	v_exp_f32_e32 v201, v201
	s_waitcnt lgkmcnt(2)
	v_mfma_f32_32x32x16_bf16 v[64:79], v[226:229], v[110:113], v[64:79]
	ds_read_b128 v[222:225], v231 offset:16512
	ds_read_b128 v[226:229], v231 offset:24704
	v_exp_f32_e32 v202, v202
	v_exp_f32_e32 v203, v203
	v_exp_f32_e32 v204, v204
	s_waitcnt lgkmcnt(3)
	v_mfma_f32_32x32x16_bf16 v[80:95], v[214:217], v[106:109], v[80:95]
	v_exp_f32_e32 v205, v205
	v_exp_f32_e32 v206, v206
	v_exp_f32_e32 v207, v207
	s_waitcnt lgkmcnt(2)
	v_mfma_f32_32x32x16_bf16 v[64:79], v[218:221], v[106:109], v[64:79]
	ds_read_b128 v[214:217], v234 offset:16512
	ds_read_b128 v[218:221], v234 offset:24704
	v_exp_f32_e32 v210, v210
	v_exp_f32_e32 v211, v211
	v_exp_f32_e32 v212, v212
	s_waitcnt lgkmcnt(3)
	v_mfma_f32_32x32x16_bf16 v[80:95], v[222:225], v[102:105], v[80:95]
	v_exp_f32_e32 v235, v208
	v_exp_f32_e32 v237, v197
	v_add_f32_e32 v197, 0, v194
	v_add_f32_e32 v197, v196, v197
	s_waitcnt lgkmcnt(2)
	v_mfma_f32_32x32x16_bf16 v[64:79], v[226:229], v[102:105], v[64:79]
	ds_read_b128 v[222:225], v213 offset:32768
	ds_read_b128 v[226:229], v213 offset:36864
	v_add_u32_e32 v213, s6, v183
	v_add_f32_e32 v197, v192, v197
	v_add_f32_e32 v197, v195, v197
	v_add_f32_e32 v197, v187, v197
	v_add_f32_e32 v197, v193, v197
	v_add_f32_e32 v197, v169, v197
	s_waitcnt lgkmcnt(3)
	v_mfma_f32_32x32x16_bf16 v[80:95], v[214:217], v[98:101], v[80:95]
	v_add_f32_e32 v197, v190, v197
	v_add_f32_e32 v197, v166, v197
	v_add_f32_e32 v197, v168, v197
	v_add_f32_e32 v197, v164, v197
	v_add_f32_e32 v197, v167, v197
	v_add_f32_e32 v197, v162, v197
	s_waitcnt lgkmcnt(2)
; #define SBAR() __builtin_amdgcn_sched_barrier(0)
; template <int OFF> DI s16x4 tr_read(int vb) { s16x4 r; asm volatile("ds_read_b64_tr_b16 %0, %1 offset:%2" : "=&v"(r) : "v"(vb), "i"(OFF) : "memory"); return r; }
; DI void finishSM(f32x16& p0, f32x16& p1, float alpha, float& l_reg, bf16x8& pa0, bf16x8& pa1, bf16x8& pa2, bf16x8& pa3) {
;     ...
;   float ps = 0;
; #pragma unroll
;   for (int r = 0; r < 16; ++r) ps += p0[r];
; #pragma unroll
;   for (int r = 0; r < 16; ++r) ps += p1[r];
;   { auto rr = __builtin_amdgcn_permlane32_swap(__float_as_uint(ps), __float_as_uint(ps), false, false);
;     ps = __uint_as_float(rr[0]) + __uint_as_float(rr[1]); }
;   l_reg = l_reg * alpha + ps;
;     ...
;   PK4(p0, 0, pa0); PK4(p0, 8, pa1); PK4(p1, 0, pa2); PK4(p1, 8, pa3);
;     ...
; }
; template <int D0> DI void pv_one(f32x16& od, int vb, bf16x8 pa0, bf16x8 pa1, bf16x8 pa2, bf16x8 pa3) {
;   const s16x4 l0 = tr_read<v_rd_off(D0, 0, 0)>(vb), h0 = tr_read<v_rd_off(D0, 0, 1)>(vb), l1 = tr_read<v_rd_off(D0, 1, 0)>(vb), h1 = tr_read<v_rd_off(D0, 1, 1)>(vb);
;   const s16x4 l2 = tr_read<v_rd_off(D0, 2, 0)>(vb), h2 = tr_read<v_rd_off(D0, 2, 1)>(vb), l3 = tr_read<v_rd_off(D0, 3, 0)>(vb), h3 = tr_read<v_rd_off(D0, 3, 1)>(vb);
;   asm volatile("s_waitcnt lgkmcnt(0)" ::: "memory"); SBAR();
;     ...
;   od = __builtin_amdgcn_mfma_f32_32x32x16_bf16(pa0, PK(l0, h0), od, 0, 0, 0);
;   od = __builtin_amdgcn_mfma_f32_32x32x16_bf16(pa1, PK(l1, h1), od, 0, 0, 0);
;   od = __builtin_amdgcn_mfma_f32_32x32x16_bf16(pa2, PK(l2, h2), od, 0, 0, 0);
;   od = __builtin_amdgcn_mfma_f32_32x32x16_bf16(pa3, PK(l3, h3), od, 0, 0, 0);
;     ...
; }
; DI void pv_d0(f32x16* o, int vb, bf16x8 pa0, bf16x8 pa1, bf16x8 pa2, bf16x8 pa3) {
;   pv_one<0>(o[0], vb, pa0, pa1, pa2, pa3); pv_one<1>(o[1], vb, pa0, pa1, pa2, pa3); pv_one<2>(o[2], vb, pa0, pa1, pa2, pa3); pv_one<3>(o[3], vb, pa0, pa1, pa2, pa3);
	v_mfma_f32_32x32x16_bf16 v[64:79], v[218:221], v[98:101], v[64:79]
	ds_read_b128 v[214:217], v213 offset:32768
	ds_read_b128 v[218:221], v213 offset:36864
	v_add_u32_e32 v213, s6, v184
	v_add_f32_e32 v197, v165, v197
	v_add_f32_e32 v197, v161, v197
	v_add_f32_e32 v197, v163, v197
	v_add_f32_e32 v197, v198, v197
	v_add_f32_e32 v197, v199, v197
	s_waitcnt lgkmcnt(3)
	v_mfma_f32_32x32x16_bf16 v[80:95], v[222:225], v[122:125], v[80:95]
	v_add_f32_e32 v197, v200, v197
	v_add_f32_e32 v197, v201, v197
	v_add_f32_e32 v197, v202, v197
	v_add_f32_e32 v197, v203, v197
	v_add_f32_e32 v197, v204, v197
	s_waitcnt lgkmcnt(2)
	v_mfma_f32_32x32x16_bf16 v[64:79], v[226:229], v[122:125], v[64:79]
	ds_read_b128 v[222:225], v213 offset:32768
	ds_read_b128 v[226:229], v213 offset:36864
	v_add_u32_e32 v213, s6, v185
	v_exp_f32_e32 v241, v209
	v_add_f32_e32 v197, v205, v197
	v_add_f32_e32 v197, v206, v197
	v_add_f32_e32 v197, v207, v197
	s_waitcnt lgkmcnt(3)
	v_mfma_f32_32x32x16_bf16 v[80:95], v[214:217], v[142:145], v[80:95]
	v_add_f32_e32 v197, v235, v197
	v_add_f32_e32 v197, v241, v197
	v_add_f32_e32 v197, v210, v197
	v_add_f32_e32 v197, v211, v197
	v_add_f32_e32 v197, v212, v197
	v_add_f32_e32 v208, v237, v197
	s_waitcnt lgkmcnt(2)
	v_mfma_f32_32x32x16_bf16 v[64:79], v[218:221], v[142:145], v[64:79]
	ds_read_b128 v[214:217], v213 offset:32768
	ds_read_b128 v[218:221], v213 offset:36864
	v_mov_b32_e32 v209, v208
	v_cvt_pk_bf16_f32 v194, v194, v196
	v_cvt_pk_bf16_f32 v195, v192, v195
	v_permlane32_swap_b32_e32 v208, v209
	v_cvt_pk_bf16_f32 v196, v187, v193
	v_cvt_pk_bf16_f32 v197, v169, v190
	s_waitcnt lgkmcnt(3)
	v_mfma_f32_32x32x16_bf16 v[80:95], v[222:225], v[118:121], v[80:95]
	v_cvt_pk_bf16_f32 v166, v166, v168
	v_cvt_pk_bf16_f32 v167, v164, v167
	v_cvt_pk_bf16_f32 v168, v162, v165
	v_cvt_pk_bf16_f32 v169, v161, v163
	v_cvt_pk_bf16_f32 v162, v198, v199
	v_cvt_pk_bf16_f32 v163, v200, v201
	s_waitcnt lgkmcnt(2)
	v_mfma_f32_32x32x16_bf16 v[64:79], v[226:229], v[118:121], v[64:79]
	v_cvt_pk_bf16_f32 v164, v202, v203
	v_cvt_pk_bf16_f32 v165, v204, v205
	v_cvt_pk_bf16_f32 v198, v206, v207
	v_cvt_pk_bf16_f32 v199, v235, v241
	v_cvt_pk_bf16_f32 v200, v210, v211
	v_cvt_pk_bf16_f32 v201, v212, v237
	s_waitcnt lgkmcnt(1)
	v_mfma_f32_32x32x16_bf16 v[80:95], v[214:217], v[138:141], v[80:95]
	v_permlane32_swap_b32_e32 v194, v196
	v_permlane32_swap_b32_e32 v195, v197
	v_permlane32_swap_b32_e32 v166, v168
	v_permlane32_swap_b32_e32 v167, v169
	v_permlane32_swap_b32_e32 v162, v164
	v_permlane32_swap_b32_e32 v163, v165
	s_waitcnt lgkmcnt(0)
	v_mfma_f32_32x32x16_bf16 v[64:79], v[218:221], v[138:141], v[64:79]
	v_add_u32_e32 v161, s42, v174
	ds_read_b64_tr_b16 v[202:203], v161 offset:0
	ds_read_b64_tr_b16 v[204:205], v161 offset:0x800
	ds_read_b64_tr_b16 v[210:211], v161 offset:0x1000
	ds_read_b64_tr_b16 v[212:213], v161 offset:0x1800
	ds_read_b64_tr_b16 v[214:215], v161 offset:0x2000
	ds_read_b64_tr_b16 v[216:217], v161 offset:0x2800
	ds_read_b64_tr_b16 v[218:219], v161 offset:0x3000
	ds_read_b64_tr_b16 v[220:221], v161 offset:0x3800
	v_permlane32_swap_b32_e32 v198, v200
	v_permlane32_swap_b32_e32 v199, v201
	v_max_f32_e32 v235, v81, v81
	v_max_f32_e32 v237, v80, v80
	v_max_f32_e32 v235, v237, v235
	s_waitcnt lgkmcnt(6)
	v_mfma_f32_32x32x16_bf16 v[0:15], v[194:197], v[202:205], v[0:15]
	ds_read_b64_tr_b16 v[202:203], v161 offset:0x200
	ds_read_b64_tr_b16 v[204:205], v161 offset:0xa00
	v_max3_f32 v235, v235, v82, v83
	v_max3_f32 v235, v235, v84, v85
	v_max3_f32 v235, v235, v86, v87
	v_max3_f32 v235, v235, v88, v89
	v_max3_f32 v235, v235, v90, v91
	v_max3_f32 v235, v235, v92, v93
	s_waitcnt lgkmcnt(6)
	v_mfma_f32_32x32x16_bf16 v[0:15], v[166:169], v[210:213], v[0:15]
	ds_read_b64_tr_b16 v[210:211], v161 offset:0x1200
	ds_read_b64_tr_b16 v[212:213], v161 offset:0x1a00
	v_max3_f32 v235, v235, v94, v95
	v_max3_f32 v235, v235, v64, v65
	v_max3_f32 v235, v235, v66, v67
	v_max3_f32 v235, v235, v68, v69
	v_max3_f32 v235, v235, v70, v71
	v_max3_f32 v235, v235, v72, v73
	s_waitcnt lgkmcnt(6)
	v_mfma_f32_32x32x16_bf16 v[0:15], v[162:165], v[214:217], v[0:15]
	ds_read_b64_tr_b16 v[214:215], v161 offset:0x2200
	ds_read_b64_tr_b16 v[216:217], v161 offset:0x2a00
	v_max3_f32 v235, v235, v74, v75
	v_max3_f32 v235, v235, v76, v77
	v_max3_f32 v235, v235, v78, v79
	v_mov_b32_e32 v237, v235
	s_waitcnt lgkmcnt(6)
	v_mfma_f32_32x32x16_bf16 v[0:15], v[198:201], v[218:221], v[0:15]
	ds_read_b64_tr_b16 v[218:219], v161 offset:0x3200
	ds_read_b64_tr_b16 v[220:221], v161 offset:0x3a00
	v_permlane32_swap_b32_e32 v235, v237
	v_max_f32_e32 v237, v237, v237
	v_max_f32_e32 v235, v235, v235
	s_waitcnt lgkmcnt(6)
	v_mfma_f32_32x32x16_bf16 v[48:63], v[194:197], v[202:205], v[48:63]
	ds_read_b64_tr_b16 v[202:203], v161 offset:0x400
	ds_read_b64_tr_b16 v[204:205], v161 offset:0xc00
	s_waitcnt lgkmcnt(6)
	v_mfma_f32_32x32x16_bf16 v[48:63], v[166:169], v[210:213], v[48:63]
	ds_read_b64_tr_b16 v[210:211], v161 offset:0x1400
	ds_read_b64_tr_b16 v[212:213], v161 offset:0x1c00
	s_waitcnt lgkmcnt(6)
	v_mfma_f32_32x32x16_bf16 v[48:63], v[162:165], v[214:217], v[48:63]
	ds_read_b64_tr_b16 v[214:215], v161 offset:0x2400
	ds_read_b64_tr_b16 v[216:217], v161 offset:0x2c00
	s_waitcnt lgkmcnt(6)
	v_mfma_f32_32x32x16_bf16 v[48:63], v[198:201], v[218:221], v[48:63]
	ds_read_b64_tr_b16 v[218:219], v161 offset:0x3400
	ds_read_b64_tr_b16 v[220:221], v161 offset:0x3c00
	s_waitcnt lgkmcnt(6)
	v_mfma_f32_32x32x16_bf16 v[32:47], v[194:197], v[202:205], v[32:47]
	ds_read_b64_tr_b16 v[202:203], v161 offset:0x600
	ds_read_b64_tr_b16 v[204:205], v161 offset:0xe00
	s_waitcnt lgkmcnt(6)
	v_mfma_f32_32x32x16_bf16 v[32:47], v[166:169], v[210:213], v[32:47]
	ds_read_b64_tr_b16 v[210:211], v161 offset:0x1600
	ds_read_b64_tr_b16 v[212:213], v161 offset:0x1e00
	s_waitcnt lgkmcnt(6)
	v_mfma_f32_32x32x16_bf16 v[32:47], v[162:165], v[214:217], v[32:47]
	ds_read_b64_tr_b16 v[214:215], v161 offset:0x2600
	ds_read_b64_tr_b16 v[216:217], v161 offset:0x2e00
	s_waitcnt lgkmcnt(6)
	v_mfma_f32_32x32x16_bf16 v[32:47], v[198:201], v[218:221], v[32:47]
	ds_read_b64_tr_b16 v[218:219], v161 offset:0x3600
	ds_read_b64_tr_b16 v[220:221], v161 offset:0x3e00
	v_max_f32_e32 v161, v235, v237
	v_sub_f32_e32 v237, v161, v160
	s_waitcnt vmcnt(0)
	s_waitcnt vmcnt(0)
	s_waitcnt lgkmcnt(0)
	s_barrier
	v_mfma_f32_32x32x16_bf16 v[16:31], v[194:197], v[202:205], v[16:31]
	v_mfma_f32_32x32x16_bf16 v[16:31], v[166:169], v[210:213], v[16:31]
	v_mfma_f32_32x32x16_bf16 v[16:31], v[162:165], v[214:217], v[16:31]
	v_mfma_f32_32x32x16_bf16 v[16:31], v[198:201], v[218:221], v[16:31]
	v_cmp_ge_f32_e32 vcc, s65, v237
	s_cmp_eq_u64 vcc, exec
	s_cselect_b64 s[38:39], -1, 0
	s_cmp_ge_u32 s12, s52
	s_cselect_b64 s[42:43], -1, 0
	s_and_b64 vcc, exec, s[42:43]
